# DN chunk2 loop batched LDS reads + moved prefetch waits; ML chunk seg2 rewritten (batched LDS reads, branch-free causal mask); phase-0 sync via XCD barrier
# speedup vs baseline: 1.0171x; 1.0171x over previous
.LBB0_249:
	s_or_b64 exec, exec, s[46:47]
	s_waitcnt lgkmcnt(0)
	s_barrier
	ds_read_b128 v[210:213], v87 offset:53248
	ds_read_b128 v[218:221], v128 offset:62464
	ds_read_b128 v[214:217], v87 offset:53312
	ds_read_b128 v[222:225], v128 offset:62528
	ds_read_b128 v[226:229], v147 offset:62464
	ds_read_b128 v[230:233], v147 offset:62528
	ds_read_b128 v[234:237], v131
	ds_read_b32 v238, v129
	ds_read_b32 v239, v148
	v_add_u32_e32 v0, v89, v153
	s_waitcnt lgkmcnt(7)
	v_mfma_f32_16x16x32_bf16 v[60:63], v[210:213], v[218:221], 0
	s_waitcnt lgkmcnt(5)
	v_mfma_f32_16x16x32_bf16 v[60:63], v[214:217], v[222:225], v[60:63]
	s_waitcnt lgkmcnt(4)
	v_mfma_f32_16x16x32_bf16 v[112:115], v[210:213], v[226:229], 0
	s_waitcnt lgkmcnt(3)
	v_mfma_f32_16x16x32_bf16 v[112:115], v[214:217], v[230:233], v[112:115]
	ds_read2st64_b32 v[2:3], v0 offset0:64 offset1:65
	ds_read2st64_b32 v[206:207], v0 offset0:66 offset1:67
	ds_read2st64_b32 v[208:209], v0 offset0:68 offset1:69
	ds_read2st64_b32 v[120:121], v0 offset0:70 offset1:71
	ds_read_b128 v[218:221], v154
	ds_read_b128 v[222:225], v155
	s_waitcnt lgkmcnt(6)
	v_add_f32_e32 v116, v234, v238
	v_add_f32_e32 v117, v235, v238
	v_add_f32_e32 v118, v236, v238
	v_add_f32_e32 v119, v237, v238
	v_add_f32_e32 v240, v234, v239
	v_add_f32_e32 v241, v235, v239
	v_add_f32_e32 v242, v236, v239
	v_add_f32_e32 v243, v237, v239
	v_mul_f32_e32 v116, 0x3fb8aa3b, v116
	v_mul_f32_e32 v117, 0x3fb8aa3b, v117
	v_mul_f32_e32 v118, 0x3fb8aa3b, v118
	v_mul_f32_e32 v119, 0x3fb8aa3b, v119
	v_mul_f32_e32 v240, 0x3fb8aa3b, v240
	v_mul_f32_e32 v241, 0x3fb8aa3b, v241
	v_mul_f32_e32 v242, 0x3fb8aa3b, v242
	v_mul_f32_e32 v243, 0x3fb8aa3b, v243
	v_exp_f32_e32 v116, v116
	v_exp_f32_e32 v117, v117
	v_exp_f32_e32 v118, v118
	v_exp_f32_e32 v119, v119
	v_exp_f32_e32 v240, v240
	v_exp_f32_e32 v241, v241
	v_exp_f32_e32 v242, v242
	v_exp_f32_e32 v243, v243
	v_mul_f32_e32 v116, v60, v116
	v_mul_f32_e32 v117, v61, v117
	v_mul_f32_e32 v118, v62, v118
	v_mul_f32_e32 v119, v63, v119
	v_mul_f32_e32 v240, v112, v240
	v_mul_f32_e32 v241, v113, v241
	v_mul_f32_e32 v242, v114, v242
	v_mul_f32_e32 v243, v115, v243
	v_cndmask_b32_e64 v116, 0, v116, s[20:21]
	v_cndmask_b32_e64 v117, 0, v117, s[22:23]
	v_cndmask_b32_e64 v118, 0, v118, s[24:25]
	v_cndmask_b32_e64 v119, 0, v119, s[26:27]
	v_cndmask_b32_e64 v240, 0, v240, s[28:29]
	v_cndmask_b32_e64 v241, 0, v241, s[30:31]
	v_cndmask_b32_e64 v242, 0, v242, s[34:35]
	v_cndmask_b32_e64 v243, 0, v243, s[36:37]
	v_cvt_pk_bf16_f32 v116, v116, v117
	v_cvt_pk_bf16_f32 v118, v118, v119
	v_cvt_pk_bf16_f32 v240, v240, v241
	v_cvt_pk_bf16_f32 v242, v242, v243
	v_add_u32_e32 v226, v130, v132
	v_add_u32_e32 v227, v130, v134
	v_add_u32_e32 v228, v130, v136
	v_add_u32_e32 v229, v130, v146
	s_waitcnt lgkmcnt(0)
	v_pk_mul_f32 v[2:3], v[2:3], v[218:219]
	v_pk_mul_f32 v[206:207], v[206:207], v[220:221]
	v_pk_mul_f32 v[208:209], v[208:209], v[222:223]
	v_pk_mul_f32 v[120:121], v[120:121], v[224:225]
	ds_write_b16 v226, v116
	ds_write_b16_d16_hi v227, v116
	ds_write_b16 v228, v118
	ds_write_b16_d16_hi v229, v118
	ds_write_b16 v149, v240
	ds_write_b16_d16_hi v150, v240
	ds_write_b16 v151, v242
	ds_write_b16_d16_hi v152, v242
	v_cvt_pk_bf16_f32 v230, v2, v3
	v_cvt_pk_bf16_f32 v231, v206, v207
	v_cvt_pk_bf16_f32 v232, v208, v209
	v_cvt_pk_bf16_f32 v233, v120, v121
	ds_write_b128 v196, v[230:233]
	v_mov_b32_e32 v0, s71
	s_waitcnt lgkmcnt(0)
	s_barrier
	ds_read_b32 v2, v0
	s_waitcnt lgkmcnt(0)
	v_mov_b32_e32 v3, v2
	s_and_saveexec_b64 s[46:47], s[38:39]
	s_cbranch_execz .LBB0_267
	ds_read_b128 v[60:63], v156 offset:53248
	ds_read_b128 v[112:115], v157
	v_add_u32_e32 v0, 0xa000, v197
	v_pk_mul_f32 v[52:53], v[52:53], v[2:3]
	s_waitcnt lgkmcnt(0)
	v_mfma_f32_16x16x32_bf16 v[60:63], v[60:63], v[112:115], 0
	ds_read_b128 v[112:115], v156 offset:53312
	ds_read_b128 v[116:119], v157 offset:64
	s_waitcnt lgkmcnt(0)
	v_mfma_f32_16x16x32_bf16 v[60:63], v[112:115], v[116:119], v[60:63]
	ds_read_b128 v[112:115], v158
	s_waitcnt lgkmcnt(0)
	s_nop 5
	v_pk_mul_f32 v[62:63], v[62:63], v[114:115]
	v_pk_mul_f32 v[60:61], v[60:61], v[112:113]
	ds_read_b128 v[112:115], v159
	ds_read_b128 v[116:119], v175
	s_waitcnt lgkmcnt(0)
	v_mfma_f32_16x16x32_bf16 v[60:63], v[112:115], v[116:119], v[60:63]
	ds_read_b128 v[112:115], v159 offset:64
	ds_read_b128 v[116:119], v175 offset:64
	s_waitcnt lgkmcnt(0)
	v_mfma_f32_16x16x32_bf16 v[60:63], v[112:115], v[116:119], v[60:63]
	s_nop 7
	ds_write2_b32 v0, v60, v61 offset1:48
	ds_write2_b32 v0, v62, v63 offset0:96 offset1:144
	v_mov_b32_e32 v60, v2
	v_mov_b32_e32 v61, v2
	v_pk_mul_f32 v[54:55], v[54:55], v[60:61]
	ds_read_b128 v[60:63], v176
	ds_read_b128 v[112:115], v175
	s_waitcnt lgkmcnt(0)
	v_mfma_f32_16x16x32_bf16 v[52:55], v[60:63], v[112:115], v[52:55]
	ds_read_b128 v[60:63], v176 offset:64
	ds_read_b128 v[112:115], v175 offset:64
	s_waitcnt lgkmcnt(0)
	v_mfma_f32_16x16x32_bf16 v[52:55], v[60:63], v[112:115], v[52:55]

.LBB0_285:
	s_or_b64 exec, exec, s[8:9]
	s_lshl_b32 s6, s2, 5
	s_and_b32 s6, s6, 0xe0
	s_bfe_u32 s7, s2, 0x50003
	s_or_b32 s8, s6, s7
	v_readlane_b32 s6, v244, 4
	v_readlane_b32 s7, v244, 5
	s_and_b64 s[6:7], s[6:7], exec
	s_cselect_b32 s18, s8, s2
	s_ashr_i32 s10, s18, 5
	s_bfe_u32 s19, s18, 0x30002
	s_ashr_i32 s11, s10, 31
	s_lshl_b32 s6, s10, 9
	s_lshl_b32 s7, s19, 6
	s_lshl_b64 s[20:21], s[10:11], 12
	s_or_b32 s12, s7, s6
	s_ashr_i32 s13, s12, 31
	v_lshl_add_u64 v[2:3], s[20:21], 0, v[46:47]
	v_lshl_add_u64 v[6:7], s[20:21], 0, v[50:51]
	v_lshl_add_u64 v[14:15], s[20:21], 0, v[56:57]
	v_lshl_add_u64 v[18:19], s[20:21], 0, v[60:61]
	s_lshl_b64 s[8:9], s[12:13], 14
	v_mad_u64_u32 v[4:5], s[6:7], v2, s87, v[48:49]
	s_lshl_b32 s62, s19, 8
	v_mad_u64_u32 v[8:9], s[6:7], v6, s87, v[52:53]
	v_mad_u64_u32 v[16:17], s[6:7], v14, s87, v[58:59]
	v_mad_u64_u32 v[20:21], s[6:7], v18, s87, v[62:63]
	s_add_u32 s6, s16, s8
	s_addc_u32 s7, s17, s9
	s_lshl_b32 s11, s18, 5
	v_lshl_add_u64 v[26:27], s[20:21], 0, v[38:39]
	s_and_b32 s11, s11, 0x60
	v_mad_u64_u32 v[28:29], s[20:21], v26, s87, v[40:41]
	v_or_b32_e32 v30, s11, v42
	v_mad_i32_i24 v29, v27, s87, v29
	v_or_b32_e32 v32, v68, v30
	v_mad_i32_i24 v9, v7, s87, v9
	v_mad_i32_i24 v21, v19, s87, v21
	v_lshl_add_u64 v[26:27], v[28:29], 0, s[62:63]
	v_mov_b32_e32 v103, v1
	v_ashrrev_i32_e32 v33, 31, v32
	v_mov_b32_e32 v31, v1
	v_mad_i32_i24 v5, v3, s87, v5
	v_lshl_add_u64 v[6:7], v[8:9], 0, s[62:63]
	v_mov_b32_e32 v99, v1
	v_mov_b32_e32 v101, v1
	v_mad_i32_i24 v17, v15, s87, v17
	v_lshl_add_u64 v[18:19], v[20:21], 0, s[62:63]
	v_lshl_add_u64 v[26:27], v[26:27], 0, v[102:103]
	v_lshlrev_b64 v[32:33], 1, v[32:33]
	v_lshl_add_u64 v[30:31], v[68:69], 0, v[30:31]
	v_lshl_add_u64 v[22:23], v[44:45], 0, s[8:9]
	v_lshl_add_u64 v[2:3], v[4:5], 0, s[62:63]
	v_mov_b32_e32 v97, v1
	v_lshl_add_u64 v[6:7], v[6:7], 0, v[98:99]
	v_lshl_add_u64 v[14:15], v[16:17], 0, s[62:63]
	v_lshl_add_u64 v[18:19], v[18:19], 0, v[98:99]
	v_lshl_add_u64 v[26:27], v[26:27], 0, v[100:101]
	v_lshl_add_u64 v[34:35], s[6:7], 0, v[32:33]
	v_lshlrev_b64 v[30:31], 1, v[30:31]
	s_lshl_b64 s[12:13], s[12:13], 2
	v_lshl_add_u64 v[2:3], v[2:3], 0, v[96:97]
	v_lshl_add_u64 v[6:7], v[6:7], 0, v[100:101]
	v_lshl_add_u64 v[10:11], v[54:55], 1, v[22:23]
	v_lshl_add_u64 v[14:15], v[14:15], 0, v[96:97]
	v_lshl_add_u64 v[18:19], v[18:19], 0, v[100:101]
	v_lshl_add_u64 v[22:23], v[64:65], 1, v[22:23]
	global_load_dwordx4 v[26:29], v[26:27], off
	s_add_u32 s20, s14, s12
	global_load_ushort v36, v[34:35], off
	v_lshl_add_u64 v[34:35], s[6:7], 0, v[30:31]
	global_load_dwordx4 v[2:5], v[2:3], off
	s_addc_u32 s21, s15, s13
	global_load_dwordx4 v[6:9], v[6:7], off
	s_mov_b32 s19, s9
	global_load_dwordx4 v[10:13], v[10:11], off
	v_lshl_add_u64 v[124:125], v[92:93], 0, s[8:9]
	global_load_dwordx4 v[14:17], v[14:15], off
	v_lshl_add_u64 v[126:127], v[94:95], 0, s[8:9]
	global_load_dwordx4 v[18:21], v[18:19], off
	s_nop 0
	global_load_dwordx4 v[22:25], v[22:23], off
	s_nop 0
	global_load_ushort v37, v[34:35], off offset:256
	global_load_ushort v97, v[34:35], off offset:512
	s_nop 0
	global_load_ushort v34, v[34:35], off offset:768
	s_waitcnt vmcnt(2)
	v_mov_b32_e32 v103, v36
	v_mov_b32_e32 v147, v37
	v_perm_b32 v99, v37, v36, s78
	global_load_dword v106, v1, s[20:21]
	s_mul_hi_i32 s21, s10, 0x2200000
	s_mul_i32 s10, s10, 0x2200000
	s_or_b32 s20, s10, s62
	s_and_b32 s10, s18, 3
	s_lshl_b32 s10, s10, 6
	s_or_b32 s18, s8, s10
	s_add_u32 s10, s12, 0x1dc80004
	s_addc_u32 s12, s13, 0
	v_lshl_add_u64 v[112:113], s[18:19], 0, v[84:85]
	s_add_u32 s18, s8, 0x4004200
	s_addc_u32 s19, s9, 0
	v_lshl_add_u64 v[118:119], s[18:19], 0, v[30:31]
	s_add_u32 s18, s8, 0x4004000
	s_addc_u32 s19, s9, 0
	v_mov_b32_e32 v30, 0
	s_waitcnt vmcnt(1)
	v_mov_b32_e32 v105, v97
	v_mov_b32_e32 v146, v34
	v_perm_b32 v97, v34, v97, s78
	v_lshl_add_u64 v[108:109], s[20:21], 0, v[80:81]
	v_lshl_add_u64 v[110:111], s[20:21], 0, v[82:83]
	v_lshl_add_u64 v[114:115], s[20:21], 0, v[86:87]
	v_lshl_add_u64 v[116:117], s[20:21], 0, v[88:89]
	v_lshl_add_u64 v[120:121], s[20:21], 0, v[90:91]
	v_lshl_add_u64 v[122:123], s[18:19], 0, v[32:33]
	s_mov_b32 s8, 63
	v_mov_b32_e32 v31, v30
	v_mov_b32_e32 v32, v30
	v_mov_b32_e32 v33, v30
	v_mov_b32_e32 v34, v30
	v_mov_b32_e32 v35, v30
	v_mov_b32_e32 v36, v30
	v_mov_b32_e32 v37, v30
	s_waitcnt vmcnt(0)
.LBB0_286:
	v_add_u32_e32 v101, v43, v107
	s_add_u32 s18, s94, s10
	s_waitcnt lgkmcnt(0)
	s_barrier
	s_waitcnt vmcnt(4)
	v_perm_b32 v99, v147, v103, s78
	v_perm_b32 v97, v146, v105, s78
	ds_write_b128 v76, v[2:5]
	ds_write_b128 v101, v[6:9] offset:34816
	ds_write_b128 v76, v[10:13] offset:53248
	ds_write_b128 v78, v[14:17]
	ds_write_b128 v145, v[18:21] offset:34816
	ds_write_b128 v78, v[22:25] offset:53248
	ds_write_b128 v129, v[26:29]
	v_lshl_add_u64 v[2:3], s[94:95], 0, v[108:109]
	v_lshl_add_u64 v[6:7], s[94:95], 0, v[110:111]
	v_lshl_add_u64 v[10:11], s[94:95], 0, v[126:127]
	v_lshl_add_u64 v[14:15], s[94:95], 0, v[114:115]
	v_lshl_add_u64 v[18:19], s[94:95], 0, v[116:117]
	v_lshl_add_u64 v[22:23], s[94:95], 0, v[124:125]
	v_lshl_add_u64 v[26:27], s[94:95], 0, v[120:121]
	v_lshl_add_u64 v[146:147], s[94:95], 0, v[122:123]
	v_lshl_add_u64 v[148:149], s[94:95], 0, v[118:119]
	s_addc_u32 s19, s95, s12
	v_mov_b32_e32 v128, v106
	global_load_dwordx4 v[2:5], v[2:3], off
	v_pk_mul_f32 v[32:33], v[32:33], v[128:129] op_sel_hi:[1,0]
	global_load_dwordx4 v[6:9], v[6:7], off
	v_pk_mul_f32 v[30:31], v[30:31], v[128:129] op_sel_hi:[1,0]
	global_load_dwordx4 v[10:13], v[10:11], off
	v_pk_mul_f32 v[36:37], v[36:37], v[128:129] op_sel_hi:[1,0]
	global_load_dwordx4 v[14:17], v[14:15], off
	v_pk_mul_f32 v[34:35], v[34:35], v[128:129] op_sel_hi:[1,0]
	global_load_dwordx4 v[18:21], v[18:19], off
	s_add_u32 s10, s10, 4
	global_load_dwordx4 v[22:25], v[22:23], off
	s_addc_u32 s12, s12, 0
	global_load_dwordx4 v[26:29], v[26:27], off
	s_add_i32 s8, s8, -1
	global_load_ushort v103, v[146:147], off
	s_nop 0
	global_load_ushort v147, v[148:149], off offset:-256
	global_load_ushort v105, v[148:149], off
	global_load_ushort v146, v[148:149], off offset:256
	global_load_dword v106, v1, s[18:19]
	s_waitcnt lgkmcnt(0)
	s_barrier
	ds_read_b128 v[180:183], v130
	ds_read_b128 v[196:199], v131 offset:53248
	ds_read_b128 v[184:187], v130 offset:64
	ds_read_b128 v[200:203], v131 offset:53312
	ds_read_b128 v[188:191], v130 offset:128
	ds_read_b128 v[208:211], v131 offset:53376
	ds_read_b128 v[192:195], v130 offset:192
	ds_read_b128 v[212:215], v131 offset:53440
	ds_read_b128 v[216:219], v131
	ds_read_b128 v[220:223], v131 offset:64
	ds_read_b128 v[224:227], v131 offset:128
	ds_read_b128 v[228:231], v131 offset:192
	v_lshl_add_u64 v[108:109], v[108:109], 0, s[56:57]
	v_lshl_add_u64 v[110:111], v[110:111], 0, s[56:57]
	v_lshl_add_u64 v[114:115], v[114:115], 0, s[56:57]
	s_waitcnt lgkmcnt(10)
	v_mfma_f32_16x16x32_bf16 v[152:155], v[196:199], v[180:183], 0
	ds_read_b128 v[232:235], v133
	v_lshl_add_u64 v[116:117], v[116:117], 0, s[56:57]
	s_waitcnt lgkmcnt(9)
	v_mfma_f32_16x16x32_bf16 v[152:155], v[200:203], v[184:187], v[152:155]
	ds_read_b128 v[236:239], v133 offset:64
	v_lshl_add_u64 v[118:119], v[118:119], 0, s[4:5]
	s_waitcnt lgkmcnt(8)
	v_mfma_f32_16x16x32_bf16 v[152:155], v[208:211], v[188:191], v[152:155]
	ds_read_b128 v[240:243], v135 offset:34816
	v_lshl_add_u64 v[120:121], v[120:121], 0, s[56:57]
	s_waitcnt lgkmcnt(7)
	v_mfma_f32_16x16x32_bf16 v[152:155], v[212:215], v[192:195], v[152:155]
	ds_read_b128 v[176:179], v135 offset:34880
	v_lshl_add_u64 v[122:123], v[122:123], 0, s[4:5]
	s_waitcnt lgkmcnt(7)
	v_mfma_f32_16x16x32_bf16 v[148:151], v[216:219], v[180:183], 0
	v_lshl_add_u64 v[124:125], v[124:125], 0, s[4:5]
	s_waitcnt lgkmcnt(6)
	v_mfma_f32_16x16x32_bf16 v[148:151], v[220:223], v[184:187], v[148:151]
	v_lshl_add_u64 v[126:127], v[126:127], 0, s[4:5]
	s_waitcnt lgkmcnt(5)
	v_mfma_f32_16x16x32_bf16 v[148:151], v[224:227], v[188:191], v[148:151]
	v_and_b32_e32 v157, 0xffff0000, v99
	s_waitcnt lgkmcnt(4)
	v_mfma_f32_16x16x32_bf16 v[148:151], v[228:231], v[192:195], v[148:151]
	v_lshlrev_b32_e32 v156, 16, v99
	v_and_b32_e32 v159, 0xffff0000, v97
	v_lshlrev_b32_e32 v158, 16, v97
	v_pk_add_f32 v[152:153], v[156:157], v[152:153] neg_lo:[0,1] neg_hi:[0,1]
	v_pk_add_f32 v[154:155], v[158:159], v[154:155] neg_lo:[0,1] neg_hi:[0,1]
	v_cvt_pk_bf16_f32 v152, v152, v153
	v_cvt_pk_bf16_f32 v153, v154, v155
	ds_write_b64 v132, v[152:153]
	s_waitcnt lgkmcnt(0)
	s_barrier
	ds_read_b128 v[180:183], v134
	ds_read_b128 v[184:187], v134 offset:64
	ds_read_b128 v[188:191], v136
	ds_read_b128 v[192:195], v136 offset:64
	ds_read_b128 v[196:199], v136 offset:2304
	ds_read_b128 v[200:203], v136 offset:2368
	s_waitcnt lgkmcnt(5)
	v_mfma_f32_16x16x32_bf16 v[148:151], v[232:235], v[180:183], v[148:151]
	v_lshl_add_u64 v[152:153], s[94:95], 0, v[112:113]
	s_waitcnt lgkmcnt(4)
	v_mfma_f32_16x16x32_bf16 v[148:151], v[236:239], v[184:187], v[148:151]
	v_lshl_add_u64 v[112:113], v[112:113], 0, s[4:5]
	s_waitcnt lgkmcnt(3)
	v_mfma_f32_16x16x32_bf16 v[30:33], v[240:243], v[188:191], v[30:33]
	s_waitcnt lgkmcnt(2)
	v_mfma_f32_16x16x32_bf16 v[30:33], v[176:179], v[192:195], v[30:33]
	s_waitcnt lgkmcnt(1)
	v_mfma_f32_16x16x32_bf16 v[34:37], v[240:243], v[196:199], v[34:37]
	s_waitcnt lgkmcnt(0)
	v_mfma_f32_16x16x32_bf16 v[34:37], v[176:179], v[200:203], v[34:37]
	s_nop 0
	v_cvt_pk_bf16_f32 v97, v148, s0
	global_store_short v[152:153], v97, off offset:-512
	v_cvt_pk_bf16_f32 v97, v149, s0
	global_store_short v[152:153], v97, off offset:-256
	v_cvt_pk_bf16_f32 v97, v150, s0
	global_store_short v[152:153], v97, off
	v_cvt_pk_bf16_f32 v97, v151, s0
	global_store_short v[152:153], v97, off offset:256
	v_cvt_pk_bf16_f32 v156, v30, v31
	v_cvt_pk_bf16_f32 v157, v32, v33
	ds_write_b64 v137, v[156:157]
	v_cvt_pk_bf16_f32 v158, v34, v35
	v_cvt_pk_bf16_f32 v159, v36, v37
	ds_write_b64 v137, v[158:159] offset:4352
	s_cmp_eq_u32 s8, 0
	s_cbranch_scc0 .LBB0_286
	s_waitcnt lgkmcnt(0)
	s_barrier
	s_waitcnt vmcnt(4)
	ds_write_b128 v76, v[2:5]
	ds_write_b128 v101, v[6:9] offset:34816
	ds_write_b128 v76, v[10:13] offset:53248
	ds_write_b128 v78, v[14:17]
	ds_write_b128 v145, v[18:21] offset:34816
	ds_write_b128 v78, v[22:25] offset:53248
	ds_write_b128 v129, v[26:29]
	s_waitcnt lgkmcnt(0)
	s_barrier
	ds_read_b128 v[2:5], v131 offset:53248
	ds_read_b128 v[6:9], v130
	ds_read_b128 v[10:13], v130 offset:64
	ds_read_b128 v[14:17], v131 offset:53312
	s_waitcnt lgkmcnt(2)
	v_mfma_f32_16x16x32_bf16 v[2:5], v[2:5], v[6:9], 0
	ds_read_b128 v[18:21], v131
	ds_read_b128 v[22:25], v131 offset:64
	v_lshlrev_b32_e32 v27, 16, v147
	v_lshlrev_b32_e32 v26, 16, v103
	s_waitcnt lgkmcnt(2)
	v_mfma_f32_16x16x32_bf16 v[2:5], v[14:17], v[10:13], v[2:5]
	ds_read_b128 v[14:17], v131 offset:53376
	s_lshl_b32 s8, s11, 1
	s_add_u32 s6, s6, s8
	s_waitcnt lgkmcnt(2)
	v_mfma_f32_16x16x32_bf16 v[6:9], v[18:21], v[6:9], 0
	s_addc_u32 s7, s7, 0
	s_add_i32 s2, s2, s50
	s_cmpk_gt_i32 s2, 0xff
	s_waitcnt lgkmcnt(1)
	v_mfma_f32_16x16x32_bf16 v[6:9], v[22:25], v[10:13], v[6:9]
	ds_read_b128 v[10:13], v131 offset:53440
	ds_read_b128 v[18:21], v130 offset:128
	ds_read_b128 v[22:25], v130 offset:192
	s_waitcnt lgkmcnt(1)
	v_mfma_f32_16x16x32_bf16 v[2:5], v[14:17], v[18:21], v[2:5]
	s_waitcnt lgkmcnt(0)
	v_mfma_f32_16x16x32_bf16 v[2:5], v[10:13], v[22:25], v[2:5]
	ds_read_b128 v[10:13], v131 offset:128
	ds_read_b128 v[14:17], v131 offset:192
	s_waitcnt lgkmcnt(1)
	v_mfma_f32_16x16x32_bf16 v[6:9], v[10:13], v[18:21], v[6:9]
	s_nop 3
	v_add_f32_e64 v2, v26, -v2
	v_add_f32_e64 v3, v27, -v3
	v_lshlrev_b32_e32 v27, 16, v146
	v_lshlrev_b32_e32 v26, 16, v105
	v_pk_add_f32 v[4:5], v[26:27], v[4:5] neg_lo:[0,1] neg_hi:[0,1]
	v_cvt_pk_bf16_f32 v2, v2, v3
	v_cvt_pk_bf16_f32 v3, v4, v5
	ds_write_b64 v132, v[2:3]
	s_waitcnt lgkmcnt(0)
	s_barrier
	ds_read_b128 v[2:5], v133
	ds_read_b128 v[10:13], v134
	ds_read_b128 v[18:21], v133 offset:64
	v_mfma_f32_16x16x32_bf16 v[6:9], v[14:17], v[22:25], v[6:9]
	ds_read_b128 v[14:17], v134 offset:64
	v_mov_b32_e32 v105, v1
	s_waitcnt lgkmcnt(2)
	v_mfma_f32_16x16x32_bf16 v[2:5], v[2:5], v[10:13], v[6:9]
	s_nop 3
	v_lshl_add_u64 v[6:7], s[6:7], 0, v[0:1]
	v_lshl_add_u64 v[6:7], v[6:7], 0, v[104:105]
	s_waitcnt lgkmcnt(0)
	v_mfma_f32_16x16x32_bf16 v[2:5], v[18:21], v[14:17], v[2:5]
	s_mov_b64 s[6:7], 0xfc000
	v_lshl_add_u64 v[108:109], v[6:7], 0, s[6:7]
	v_lshl_add_u64 v[6:7], v[66:67], 1, v[108:109]
	s_waitcnt vmcnt(4)
	v_pk_mul_f32 v[20:21], v[106:107], v[32:33] op_sel_hi:[0,1]
	v_pk_mul_f32 v[18:19], v[106:107], v[30:31] op_sel_hi:[0,1]
	s_nop 1
	v_cvt_pk_bf16_f32 v2, v2, s0
	global_store_short v[6:7], v2, off
	ds_read_b128 v[6:9], v135 offset:34816
	v_cvt_pk_bf16_f32 v10, v3, s0
	v_lshl_add_u64 v[2:3], v[70:71], 1, v[108:109]
	global_store_short v[2:3], v10, off
	ds_read_b128 v[10:13], v135 offset:34880
	ds_read_b128 v[14:17], v136
	ds_read_b128 v[22:25], v136 offset:64
	s_waitcnt lgkmcnt(1)
	v_mfma_f32_16x16x32_bf16 v[14:17], v[6:9], v[14:17], v[18:21]
	s_nop 2
	ds_read_b128 v[18:21], v136 offset:2304
	ds_read_b128 v[26:29], v136 offset:2368
	v_cvt_pk_bf16_f32 v4, v4, s0
	s_waitcnt lgkmcnt(2)
	v_mfma_f32_16x16x32_bf16 v[14:17], v[10:13], v[22:25], v[14:17]
	v_mul_f32_e64 v24, v106, v36
	v_mul_f32_e64 v25, v106, v37
	v_pk_mul_f32 v[22:23], v[106:107], v[34:35] op_sel_hi:[0,1]
	v_lshl_add_u64 v[2:3], v[72:73], 1, v[108:109]
	global_store_short v[2:3], v4, off
	s_waitcnt lgkmcnt(1)
	v_mfma_f32_16x16x32_bf16 v[6:9], v[6:9], v[18:21], v[22:25]
	v_cvt_pk_bf16_f32 v4, v5, s0
	v_lshl_add_u64 v[2:3], v[74:75], 1, v[108:109]
	global_store_short v[2:3], v4, off
	s_waitcnt lgkmcnt(0)
	v_mfma_f32_16x16x32_bf16 v[2:5], v[10:13], v[26:29], v[6:9]
	s_nop 2
	v_cvt_pk_bf16_f32 v6, v14, v15
	v_cvt_pk_bf16_f32 v7, v16, v17
	s_nop 2
	v_cvt_pk_bf16_f32 v2, v2, v3
	v_cvt_pk_bf16_f32 v3, v4, v5
	ds_write_b64 v137, v[6:7]
	ds_write_b64 v137, v[2:3] offset:4352
	s_cbranch_scc0 .LBB0_282

.LBB0_470:
	s_and_b64 vcc, exec, s[8:9]
	s_cbranch_vccz .LBB0_9
	s_add_i32 s2, s48, 1
	s_cmp_ge_i32 s2, s49
	s_cbranch_scc1 .LBB0_9
	v_readlane_b32 s6, v244, 49
	v_readlane_b32 s7, v244, 50
	s_and_b64 vcc, exec, s[6:7]
	s_getreg_b32 s2, hwreg(HW_REG_XCC_ID, 0, 4)
	s_waitcnt vmcnt(0)
	s_waitcnt vmcnt(0) lgkmcnt(0)
	s_barrier
	s_mov_b64 s[6:7], exec
	v_readlane_b32 s8, v244, 2
	v_readlane_b32 s9, v244, 3
	s_and_b64 s[8:9], s[6:7], s[8:9]
	s_mov_b64 exec, s[8:9]
	s_cbranch_execz .LBB0_612
	v_readlane_b32 s8, v244, 33
	s_load_dwordx2 s[0:1], s[0:1], 0x100
	s_waitcnt vmcnt(0) expcnt(0) lgkmcnt(0)
	v_mov_b32_e32 v0, s8
	ds_read_b32 v3, v0
	v_readlane_b32 s8, v244, 34
	s_and_b32 s2, s2, 15
	s_waitcnt lgkmcnt(0)
	v_cmp_ne_u32_e32 vcc, 0, v3
	v_mov_b32_e32 v0, s8
	ds_read_b32 v2, v0
	s_cbranch_vccnz .LBB0_490
	s_add_u32 s8, s0, 0x1de80200
	s_addc_u32 s9, s1, 0
	s_add_u32 s10, s0, 0x1de80400
	s_addc_u32 s11, s1, 0
	s_add_u32 s12, s0, 0x1de80500
	s_addc_u32 s13, s1, 0
	s_add_u32 s14, s0, 0x1de80600
	s_addc_u32 s15, s1, 0
	s_add_u32 s16, s0, 0x1de80700
	s_addc_u32 s17, s1, 0
	s_add_u32 s18, s0, 0x1de80800
	s_addc_u32 s19, s1, 0
	s_add_u32 s20, s0, 0x1de80900
	s_addc_u32 s21, s1, 0
	s_add_u32 s22, s0, 0x1de80a00
	s_addc_u32 s23, s1, 0
	s_add_u32 s24, s0, 0x1de80b00
	s_addc_u32 s25, s1, 0
	s_add_u32 s26, s0, 0x1de80c00
	s_addc_u32 s27, s1, 0
	s_add_u32 s28, s0, 0x1de80d00
	s_addc_u32 s29, s1, 0
	s_add_u32 s30, s0, 0x1de80e00
	s_addc_u32 s31, s1, 0
	s_add_u32 s34, s0, 0x1de80f00
	s_addc_u32 s35, s1, 0
	s_add_u32 s36, s0, 0x1de81000
	s_addc_u32 s37, s1, 0
	s_add_u32 s38, s0, 0x1de81100
	s_addc_u32 s39, s1, 0
	s_add_u32 s40, s0, 0x1de81200
	s_addc_u32 s41, s1, 0
	s_add_u32 s42, s0, 0x1de81300
	s_addc_u32 s43, s1, 0
	s_mov_b32 s54, 1
	s_branch .LBB0_477
